# phase E setup: rel_bias table staged in LDS once, bias-table build reads LDS instead of 7 dependent global loads per thread
# speedup vs baseline: 1.0497x; 1.0027x over previous
; #define LAS __attribute__((address_space(3)))
; __device__ __forceinline__ float wave_max(float v) { v = fmaxf(v, __shfl_xor(v, 1)); v = fmaxf(v, __shfl_xor(v, 2)); v = fmaxf(v, __shfl_xor(v, 4)); v = fmaxf(v, __shfl_xor(v, 8)); v = fmaxf(v, __shfl_xor(v, 16)); v = fmaxf(v, __shfl_xor(v, 32)); return v; }
; #define INP(k) ({ int k_ = (k); LAUNDER_S(k_); (const float*)(const GAS float*)P.in[k_]; })
; __global__ void __launch_bounds__(512, 2) hybrid_fwd(Params P) {
;     ...
;             LAS unsigned* misc = (LAS unsigned*)(lds + ATT_MISC); LAS float* btab = (LAS float*)(lds + ATT_BT);
;             const float* rel_bias = INP(1);
;             __syncthreads();
;             if (wave == 0) { const float* mqn = INP(4) + L * 64; const float* mkn = INP(5) + L * 64; const float* nqn = INP(6) + L * 64; const float* nkn = INP(7) + L * 192;
;                 float gq = fmaxf(fabsf(mqn[lane]), fabsf(nqn[lane])); float gk = fmaxf(fmaxf(fabsf(mkn[lane]), fabsf(nkn[lane])), fmaxf(fabsf(nkn[64 + lane]), fabsf(nkn[128 + lane])));
;                 float bm = 0.f;
; #pragma unroll
;                 for (int i = 0; i < 6; ++i) bm = fmaxf(bm, fabsf(rel_bias[lane + 64 * i]));
;                 gq = wave_max(gq); gk = wave_max(gk); bm = wave_max(bm);
;                 if (lane == 0) ((LAS float*)misc)[2] = 8.0f * gq * gk + bm; }
.LBB0_794:
	s_nop 0
	s_nop 0
	s_nop 0
	s_nop 0
	s_nop 0
	s_nop 0
	s_nop 0
	s_or_b64 exec, exec, s[4:5]
	v_readlane_b32 s4, v255, 17
	s_mov_b64 s[6:7], s[58:59]
	s_mov_b32 s5, s69
	s_barrier
	s_mov_b32 s5, s2
	v_mov_b32_e32 v210, v146
	s_mov_b32 s8, 1
	s_ashr_i32 s9, s8, 31
	s_lshl_b64 s[8:9], s[8:9], 3
	s_add_u32 s8, s0, s8
	s_addc_u32 s9, s1, s9
	s_load_dwordx2 s[8:9], s[8:9], 0x0
	s_waitcnt lgkmcnt(0)
	v_lshlrev_b32_e32 v253, 2, v210
	v_cmp_gt_u32_e32 vcc, 0x180, v210
	s_and_saveexec_b64 s[98:99], vcc
	global_load_dword v252, v253, s[8:9]
	s_mov_b64 exec, s[98:99]
	s_nop 3
	v_readfirstlane_b32 s5, v210
	s_cmp_lt_u32 s5, 64
	s_waitcnt lgkmcnt(0)
	s_barrier
	s_cbranch_scc0 .LBB0_798
	s_mov_b32 s10, 4
	s_ashr_i32 s11, s10, 31
	s_lshl_b64 s[10:11], s[10:11], 3
	s_add_u32 s10, s0, s10
	s_addc_u32 s11, s1, s11
	s_load_dwordx2 s[12:13], s[10:11], 0x0
	s_lshl_b32 s10, s4, 6
	s_ashr_i32 s11, s10, 31
	s_lshl_b64 s[10:11], s[10:11], 2
	s_mov_b32 s14, 5
	s_waitcnt lgkmcnt(0)
	s_add_u32 s12, s12, s10
	s_addc_u32 s13, s13, s11
	s_ashr_i32 s15, s14, 31
	s_lshl_b64 s[14:15], s[14:15], 3
	s_add_u32 s14, s0, s14
	s_addc_u32 s15, s1, s15
	s_load_dwordx2 s[14:15], s[14:15], 0x0
	s_mov_b32 s16, 6
	v_and_b32_e32 v0, 63, v210
	v_lshlrev_b32_e32 v1, 2, v0
	s_waitcnt lgkmcnt(0)
	s_add_u32 s18, s14, s10
	s_addc_u32 s19, s15, s11
	s_ashr_i32 s17, s16, 31
	s_lshl_b64 s[14:15], s[16:17], 3
	s_add_u32 s14, s0, s14
	s_addc_u32 s15, s1, s15
	s_load_dwordx2 s[14:15], s[14:15], 0x0
	s_mov_b32 s16, 7
	global_load_dword v2, v1, s[18:19]
	global_load_dword v3, v1, s[8:9]
	global_load_dword v4, v1, s[8:9] offset:256
	global_load_dword v5, v1, s[8:9] offset:512
	global_load_dword v6, v1, s[8:9] offset:768
	global_load_dword v7, v1, s[8:9] offset:1024
	global_load_dword v8, v1, s[8:9] offset:1280
	global_load_dword v9, v1, s[12:13]
	s_mul_i32 s12, s4, 0xc0
	s_waitcnt lgkmcnt(0)
	s_add_u32 s10, s14, s10
	s_addc_u32 s11, s15, s11
	s_ashr_i32 s17, s16, 31
	global_load_dword v10, v1, s[10:11]
	s_lshl_b64 s[10:11], s[16:17], 3
	s_add_u32 s10, s0, s10
	s_addc_u32 s11, s1, s11
	s_load_dwordx2 s[10:11], s[10:11], 0x0
	s_ashr_i32 s13, s12, 31
	s_lshl_b64 s[12:13], s[12:13], 2
	v_mbcnt_hi_u32_b32 v13, -1, v167
	v_and_b32_e32 v15, 64, v13
	s_waitcnt lgkmcnt(0)
	s_add_u32 s10, s10, s12
	s_addc_u32 s11, s11, s13
	global_load_dword v11, v1, s[10:11] offset:512
	global_load_dword v12, v1, s[10:11] offset:256
	s_nop 0
	global_load_dword v1, v1, s[10:11]
	v_xor_b32_e32 v14, 1, v13
	v_add_u32_e32 v15, 64, v15
	v_cmp_lt_i32_e32 vcc, v14, v15
	v_xor_b32_e32 v16, 2, v13
	v_xor_b32_e32 v17, 4, v13
	v_cndmask_b32_e32 v14, v13, v14, vcc
	v_lshlrev_b32_e32 v14, 2, v14
	v_cmp_lt_i32_e32 vcc, v16, v15
	v_xor_b32_e32 v18, 8, v13
	v_xor_b32_e32 v19, 16, v13
	v_cndmask_b32_e32 v16, v13, v16, vcc
	v_cmp_lt_i32_e32 vcc, v17, v15
	v_xor_b32_e32 v20, 32, v13
	s_waitcnt vmcnt(9)
	v_max3_f32 v3, |v3|, 0, |v4|
	v_cndmask_b32_e32 v17, v13, v17, vcc
	s_waitcnt vmcnt(7)
	v_max3_f32 v3, v3, |v5|, |v6|
	v_cmp_lt_i32_e32 vcc, v18, v15
	s_waitcnt vmcnt(5)
	v_max3_f32 v3, v3, |v7|, |v8|
	ds_bpermute_b32 v4, v14, v3
	v_cndmask_b32_e32 v18, v13, v18, vcc
	v_cmp_lt_i32_e32 vcc, v19, v15
	s_waitcnt vmcnt(4)
	v_max_f32_e64 v6, |v9|, |v9|
	v_lshlrev_b32_e32 v5, 2, v18
	s_waitcnt lgkmcnt(0)
	v_max_f32_e32 v4, v4, v4
	v_cndmask_b32_e32 v19, v13, v19, vcc
	v_cmp_lt_i32_e32 vcc, v20, v15
	v_lshlrev_b32_e32 v15, 2, v16
	v_max_f32_e32 v3, v3, v4
	ds_bpermute_b32 v4, v15, v3
	s_waitcnt vmcnt(3)
	v_max_f32_e64 v7, |v10|, |v10|
	v_max_f32_e32 v6, v6, v7
	ds_bpermute_b32 v7, v14, v6
	v_lshlrev_b32_e32 v16, 2, v17
	s_waitcnt lgkmcnt(1)
	v_max_f32_e32 v4, v4, v4
	v_max_f32_e32 v3, v3, v4
	s_waitcnt vmcnt(2)
	v_max_f32_e64 v4, |v11|, |v11|
	s_waitcnt vmcnt(1)
	v_max_f32_e64 v10, |v12|, |v12|
	v_max_f32_e32 v4, v10, v4
	s_waitcnt vmcnt(0)
	v_max3_f32 v1, |v2|, |v1|, v4
	ds_bpermute_b32 v2, v14, v1
	s_waitcnt lgkmcnt(1)
	v_max_f32_e32 v7, v7, v7
	v_max_f32_e32 v6, v6, v7
	ds_bpermute_b32 v7, v15, v6
	ds_bpermute_b32 v11, v16, v3
	s_waitcnt lgkmcnt(2)
	v_max_f32_e32 v2, v2, v2
	v_max_f32_e32 v1, v1, v2
	ds_bpermute_b32 v2, v15, v1
	s_waitcnt lgkmcnt(2)
	v_max_f32_e32 v4, v7, v7
	v_max_f32_e32 v4, v6, v4
	s_waitcnt lgkmcnt(1)
	v_max_f32_e32 v6, v11, v11
	ds_bpermute_b32 v7, v16, v4
	s_waitcnt lgkmcnt(1)
	v_max_f32_e32 v2, v2, v2
	v_max_f32_e32 v1, v1, v2
	v_max_f32_e32 v3, v3, v6
	ds_bpermute_b32 v2, v16, v1
	ds_bpermute_b32 v6, v5, v3
	s_waitcnt lgkmcnt(2)
	v_max_f32_e32 v7, v7, v7
	v_max_f32_e32 v4, v4, v7
	ds_bpermute_b32 v7, v5, v4
	s_waitcnt lgkmcnt(2)
	v_max_f32_e32 v2, v2, v2
	s_waitcnt lgkmcnt(1)
	v_max_f32_e32 v6, v6, v6
	v_max_f32_e32 v1, v1, v2
	v_lshlrev_b32_e32 v8, 2, v19
	v_max_f32_e32 v3, v3, v6
	ds_bpermute_b32 v2, v5, v1
	ds_bpermute_b32 v6, v8, v3
	s_waitcnt lgkmcnt(2)
	v_max_f32_e32 v5, v7, v7
	v_max_f32_e32 v4, v4, v5
	v_cndmask_b32_e32 v13, v13, v20, vcc
	s_waitcnt lgkmcnt(1)
	v_max_f32_e32 v2, v2, v2
	s_waitcnt lgkmcnt(0)
	v_max_f32_e32 v5, v6, v6
	ds_bpermute_b32 v6, v8, v4
	v_max_f32_e32 v2, v1, v2
	ds_bpermute_b32 v7, v8, v2
	v_max_f32_e32 v1, v3, v5
	v_lshlrev_b32_e32 v9, 2, v13
	s_waitcnt lgkmcnt(1)
	v_max_f32_e32 v3, v6, v6
	v_max_f32_e32 v3, v4, v3
	s_waitcnt lgkmcnt(0)
	v_max_f32_e32 v4, v7, v7
	v_max_f32_e32 v2, v2, v4
	ds_bpermute_b32 v5, v9, v3
	ds_bpermute_b32 v4, v9, v2
	ds_bpermute_b32 v6, v9, v1
	v_cmp_eq_u32_e32 vcc, 0, v0
	s_and_saveexec_b64 s[10:11], vcc
	s_cbranch_execz .LBB0_797
	s_waitcnt lgkmcnt(2)
	v_max_f32_e32 v0, v5, v5
	v_max_f32_e32 v3, v3, v3
	v_max_f32_e32 v0, v3, v0
	s_waitcnt lgkmcnt(1)
	v_max_f32_e32 v3, v4, v4
	v_max_f32_e32 v2, v2, v2
	v_max_f32_e32 v2, v2, v3
	s_waitcnt lgkmcnt(0)
	v_max_f32_e32 v3, v6, v6
	v_max_f32_e32 v1, v1, v1
	v_mul_f32_e32 v0, 0x41000000, v0
	v_max_f32_e32 v1, v1, v3
	v_fmac_f32_e32 v1, v0, v2
	ds_write_b32 v165, v1 offset:50696

; #define LAS __attribute__((address_space(3)))
; __global__ void __launch_bounds__(512, 2) hybrid_fwd(Params P) {
;     ...
;             __syncthreads();
;             const float shift = ((LAS float*)misc)[2];
;             for (int i = tid; i < 12 * BT_N; i += 512) { const int hd = i / BT_N, jx = i - hd * BT_N; const int d = jx - 64;
;                 float v = -3.0e38f;
;                 if (d >= 0) { int bk; if (d < 16) bk = d; else if (d >= 128) bk = 31; else { bk = 16 + (int)(__log2f((float)d * (1.0f / 16.0f)) * (16.0f / 3.0f)); bk = bk > 31 ? 31 : bk; }
;                     v = (rel_bias[bk * 12 + hd] - shift) * L2E; }
;                 btab[i] = v; }
.LBB0_798:
	s_movk_i32 s10, 0x180
	v_cmp_gt_u32_e64 s[98:99], s10, v210
	s_waitcnt vmcnt(0)
	s_and_saveexec_b64 s[10:11], s[98:99]
	ds_write_b32 v253, v252 offset:60000
	s_mov_b64 exec, s[10:11]
	s_movk_i32 s5, 0xd80
	v_cmp_gt_i32_e32 vcc, s5, v210
	s_waitcnt lgkmcnt(0)
	s_barrier
	s_and_saveexec_b64 s[10:11], vcc
	s_cbranch_execz .LBB0_805
	ds_read_b32 v1, v165 offset:50696
	s_add_i32 s5, s66, 0x100
	v_lshl_add_u32 v2, v210, 2, s5
	s_mov_b64 s[12:13], 0
	v_mov_b32_e32 v3, v210
	s_branch .LBB0_802
.LBB0_800:
	s_or_b64 exec, exec, s[16:17]
	s_waitcnt lgkmcnt(0)
	v_mad_u64_u32 v[4:5], s[16:17], v5, 12, v[0:1]
	v_lshlrev_b32_e32 v4, 2, v4
	ds_read_b32 v0, v4 offset:60000
	s_waitcnt lgkmcnt(0)
	v_sub_f32_e32 v0, v0, v1
	v_mul_f32_e32 v5, 0x3fb8aa3b, v0
